# M3 tail: PV staged through LDS once per workgroup (double-buffered), looped heads
# baseline (speedup 1.0000x reference)
; DI f32x4 mfma16(bf16x8 a, bf16x8 b, f32x4 c) { return __builtin_amdgcn_mfma_f32_16x16x32_bf16(a, b, c, 0, 0, 0); }
; __global__ void __launch_bounds__(512, 2) fwd_megakernel(Args args) {
;     ...
;                 {
;                     const int lrow = 16 * wave + r16;
;                     bf16x8 ca[4];
; #pragma unroll
;                     for (int ks = 0; ks < 4; ++ks) ca[ks] = lds_frag(Cs, lrow, 136, ks * 32 + q4 * 8);
;                     f32x4 cbr[8];
; #pragma unroll
;                     for (int st = 0; st < 8; ++st) {
;                         cbr[st] = (f32x4){0.f, 0.f, 0.f, 0.f};
;                         if (st <= wave) {
; #pragma unroll
;                             for (int ks = 0; ks < 4; ++ks) cbr[st] = mfma16(ca[ks], lds_frag(Bs, 16 * st + r16, 136, ks * 32 + q4 * 8), cbr[st]);
;                         }
;                     }
;                     __syncthreads();
; #pragma unroll 1
;                     for (int hh = 0; hh < 4; ++hh) {
;                         const int h = g2 * 4 + hh; const int unit8 = ((b * NCH + c) * 8) + h;
;                         bf16x8 pvf[4][4];
;                         {
;                             const bf16* pv = PV + (size_t)unit8 * 8192;
; #pragma unroll
;                             for (int ks = 0; ks < 4; ++ks)
; #pragma unroll
;                                 for (int pt = 0; pt < 4; ++pt) pvf[ks][pt] = *(const bf16x8*)(pv + (16 * pt + r16) * 128 + ks * 32 + q4 * 8);
.LBB0_973:
	s_waitcnt vmcnt(0) lgkmcnt(0)
	s_mov_b32 s78, s91
	s_mov_b64 s[90:91], s[92:93]
	s_mov_b64 s[92:93], s[84:85]
	s_mov_b64 s[84:85], s[94:95]
	s_mov_b64 s[96:97], s[28:29]
	s_mov_b32 s79, s59
	s_mov_b32 s33, s86
	s_lshr_b32 s2, s86, 4
	v_and_b32_e32 v176, 15, v232
	v_bfe_u32 v177, v232, 4, 2
	v_mul_u32_u24_e32 v178, 0x110, v176
	v_lshl_add_u32 v178, v177, 4, v178
	s_mul_i32 s4, s2, 0x1100
	v_add_u32_e32 v179, s4, v178
	v_readlane_b32 s24, v251, 31
	v_readlane_b32 s25, v251, 32
	v_readlane_b32 s5, v253, 58
	s_and_b32 s6, s83, 1
	s_lshl_b32 s7, s6, 2
	s_add_i32 s5, s5, s7
	s_lshl_b32 s5, s5, 2
	s_add_u32 s24, s24, s5
	s_addc_u32 s25, s25, 0
	s_load_dwordx4 s[36:39], s[24:25], 0x0
	s_lshl_b32 s7, s83, 16
	s_add_u32 s8, s80, 0x12000000
	s_addc_u32 s9, s81, 0
	s_add_u32 s8, s8, s7
	s_addc_u32 s9, s9, 0
	s_mov_b64 s[34:35], s[8:9]
	v_lshlrev_b32_e32 v196, 8, v176
	v_lshl_add_u32 v196, v177, 4, v196
	v_add_u32_e32 v197, 0x1000, v196
	v_add_u32_e32 v198, 0x2000, v196
	v_add_u32_e32 v199, 0x3000, v196
	s_lshr_b32 s7, s83, 1
	s_mul_i32 s12, s7, 0xb0000
	s_lshl_b32 s13, s6, 9
	s_add_u32 s12, s12, s13
	s_add_u32 s10, s80, 0x15000000
	s_addc_u32 s11, s81, 0
	s_add_u32 s10, s10, s12
	s_addc_u32 s11, s11, 0
	s_lshl_b32 s12, s7, 18
	s_add_u32 s12, s12, s13
	s_add_u32 s22, s80, 0xa000000
	s_addc_u32 s23, s81, 0
	s_add_u32 s12, s22, s12
	s_addc_u32 s13, s23, 0
	s_lshl_b32 s22, s6, 19
	s_lshl_b32 s23, s7, 11
	s_add_u32 s22, s22, s23
	s_add_u32 s26, s80, 0x300000
	s_addc_u32 s27, s81, 0
	s_add_u32 s22, s26, s22
	s_addc_u32 s23, s27, 0
	v_lshlrev_b32_e32 v180, 8, v176
	v_lshl_add_u32 v180, v177, 4, v180
	v_lshl_add_u32 v183, s2, 3, v177
	v_lshlrev_b32_e32 v182, 8, v183
	v_lshl_add_u32 v182, v176, 4, v182
	v_mul_u32_u24_e32 v183, 0x110, v183
	v_lshl_add_u32 v183, v176, 4, v183
	v_lshl_add_u32 v213, s2, 4, v176
	v_mul_u32_u24_e32 v184, 0x1600, v213
	v_lshl_add_u32 v184, v177, 3, v184
	v_lshlrev_b32_e32 v185, 11, v213
	v_lshl_add_u32 v185, v177, 3, v185
	v_lshlrev_b32_e32 v186, 4, v213
	v_lshlrev_b32_e32 v187, 2, v213
	v_add_u32_e32 v187, 0x22000, v187
	v_lshlrev_b32_e32 v188, 4, v177
	v_add_u32_e32 v188, 0x22000, v188
	v_mul_u32_u24_e32 v189, 0x110, v213
	v_lshl_add_u32 v189, v177, 3, v189
	v_add_u32_e32 v189, 0x8800, v189
	v_add_u32_e32 v190, 0x11000, v178
	v_mul_u32_u24_e32 v191, 0x440, v177
	v_lshl_add_u32 v191, v213, 1, v191
	v_add_u32_e32 v191, 0x11000, v191
	v_mov_b32_e32 v214, 0
	v_mov_b32_e32 v215, 0
	v_and_b32_e32 v213, 63, v232
	v_xor_b32_e32 v211, 16, v213
	v_lshlrev_b32_e32 v211, 2, v211
	v_xor_b32_e32 v212, 32, v213
	v_lshlrev_b32_e32 v212, 2, v212
	v_lshlrev_b32_e32 v213, 2, v177
	v_add_u32_e32 v160, 0, v213
	v_cmp_le_u32_e64 s[44:45], v160, v176
	v_add_u32_e32 v160, 1, v213
	v_cmp_le_u32_e64 s[46:47], v160, v176
	v_add_u32_e32 v160, 2, v213
	v_cmp_le_u32_e64 s[48:49], v160, v176
	v_add_u32_e32 v160, 3, v213
	v_cmp_le_u32_e64 s[50:51], v160, v176
	v_cmp_eq_u32_e64 s[42:43], 0, v177
	s_waitcnt vmcnt(0) lgkmcnt(0)
	s_barrier
	global_load_dwordx4 v[196:199], v182, s[8:9]
	global_load_dwordx4 v[234:237], v182, s[8:9] offset:1024
	global_load_dwordx2 v[128:129], v184, s[10:11] offset:0
	global_load_dwordx2 v[130:131], v184, s[10:11] offset:32
	global_load_dwordx2 v[132:133], v184, s[10:11] offset:64
	global_load_dwordx2 v[134:135], v184, s[10:11] offset:96
	ds_read_b128 v[32:35], v179 offset:0
	ds_read_b128 v[36:39], v179 offset:64
	ds_read_b128 v[40:43], v179 offset:128
	ds_read_b128 v[44:47], v179 offset:192
	ds_read_b128 v[160:163], v178 offset:34816
	ds_read_b128 v[164:167], v178 offset:34880
	ds_read_b128 v[168:171], v178 offset:34944
	ds_read_b128 v[172:175], v178 offset:35008
	s_cmp_lt_u32 s2, 1
	s_cbranch_scc1 .Lm3_cb_last0
	ds_read_b128 v[136:139], v178 offset:39168
	ds_read_b128 v[140:143], v178 offset:39232
	ds_read_b128 v[144:147], v178 offset:39296
	ds_read_b128 v[148:151], v178 offset:39360
	s_waitcnt lgkmcnt(4)
	v_mfma_f32_16x16x32_bf16 v[0:3], v[160:163], v[32:35], 0
	v_mfma_f32_16x16x32_bf16 v[0:3], v[164:167], v[36:39], v[0:3]
	v_mfma_f32_16x16x32_bf16 v[0:3], v[168:171], v[40:43], v[0:3]
	v_mfma_f32_16x16x32_bf16 v[0:3], v[172:175], v[44:47], v[0:3]
	s_branch .Lm3_cb_next0

; #define LAS __attribute__((address_space(3)))
; DI unsigned short f2bf(float f) { return (unsigned short)(pk2(f, 0.f) & 0xffffu); }
; __global__ void __launch_bounds__(512, 2) fwd_megakernel(Args args) {
;     ...
;                     __syncthreads();
; #pragma unroll 1
;                     for (int hh = 0; hh < 4; ++hh) {
;                         const int h = g2 * 4 + hh; const int unit8 = ((b * NCH + c) * 8) + h;
;                         bf16x8 pvf[4][4];
;                         {
;                             const bf16* pv = PV + (size_t)unit8 * 8192;
; #pragma unroll
;                             for (int ks = 0; ks < 4; ++ks)
; #pragma unroll
;                                 for (int pt = 0; pt < 4; ++pt) pvf[ks][pt] = *(const bf16x8*)(pv + (16 * pt + r16) * 128 + ks * 32 + q4 * 8);
;                         }
;                         bf16 zr[4][4];
; #pragma unroll
;                         for (int j = 0; j < 4; ++j)
; #pragma unroll
;                             for (int pt = 0; pt < 4; ++pt) zr[j][pt] = proj[(grow0 + 16 * wave + q4 * 4 + j) * NPROJ + PC_Z + h * 64 + 16 * pt + r16];
;                         const LAS float* hdt = s_dt + hh * 128; const LAS float* hacs = s_acs + hh * 128;
;                         float acl[4];
; #pragma unroll
;                         for (int j = 0; j < 4; ++j) acl[j] = hacs[16 * wave + q4 * 4 + j];
; #pragma unroll
;                         for (int st = 0; st < 8; ++st) {
;                             if (st <= (wave | 1)) {
;                                 const int sI = 16 * st + r16; const float acss = hacs[sI], dts = hdt[sI];
; #pragma unroll
;                                 for (int j = 0; j < 4; ++j) { const int l = 16 * wave + q4 * 4 + j; const float mv = (sI <= l) ? cbr[st][j] * __expf(fminf(acl[j] - acss, 0.f)) * dts : 0.f; Ms[l * 136 + sI] = f2bf(mv); }
;                             }
.Lm3_cb_done:
	s_waitcnt lgkmcnt(0)
	s_barrier
	s_waitcnt vmcnt(0)
	ds_write_b128 v183, v[196:199]
	ds_write_b128 v183, v[234:237] offset:1088
	s_mov_b32 s28, 0
	s_mov_b32 s3, 0
.Lm3_head:
	s_cmp_eq_u32 s3, 3
	s_cbranch_scc1 .Lm3_nopf
	s_add_u32 s8, s8, 0x4000
	s_addc_u32 s9, s9, 0
	global_load_dwordx4 v[196:199], v182, s[8:9]
	global_load_dwordx4 v[234:237], v182, s[8:9] offset:1024
.Lm3_nopf:
	ds_read_b32 v206, v187 offset:2048
	ds_read_b128 v[152:155], v188 offset:2048
	ds_read_b128 v[156:159], v188 offset:0
	s_cmp_eq_u32 s2, 0
	s_cselect_b64 s[52:53], s[44:45], -1
	s_cselect_b64 s[54:55], s[46:47], -1
	s_cselect_b64 s[56:57], s[48:49], -1
	s_cselect_b64 s[58:59], s[50:51], -1
	s_waitcnt lgkmcnt(0)
	v_sub_f32_e32 v160, v206, v152
	v_sub_f32_e32 v161, v206, v153
	v_sub_f32_e32 v162, v206, v154
	v_sub_f32_e32 v163, v206, v155
	v_min_f32_e32 v160, 0, v160
	v_min_f32_e32 v161, 0, v161
	v_min_f32_e32 v162, 0, v162
	v_min_f32_e32 v163, 0, v163
	v_mul_f32_e32 v160, 0x3fb8aa3b, v160
	v_mul_f32_e32 v161, 0x3fb8aa3b, v161
	v_mul_f32_e32 v162, 0x3fb8aa3b, v162
	v_mul_f32_e32 v163, 0x3fb8aa3b, v163
	v_exp_f32_e32 v160, v160
	v_exp_f32_e32 v161, v161
	v_exp_f32_e32 v162, v162
	v_exp_f32_e32 v163, v163
	s_nop 0
	v_mul_f32_e32 v160, v0, v160
	v_mul_f32_e32 v161, v1, v161
	v_mul_f32_e32 v162, v2, v162
	v_mul_f32_e32 v163, v3, v163
	v_mul_f32_e32 v160, v160, v156
	v_mul_f32_e32 v161, v161, v157
	v_mul_f32_e32 v162, v162, v158
	v_mul_f32_e32 v163, v163, v159
	v_cndmask_b32_e64 v160, 0, v160, s[52:53]
	v_cndmask_b32_e64 v161, 0, v161, s[54:55]
	v_cndmask_b32_e64 v162, 0, v162, s[56:57]
	v_cndmask_b32_e64 v163, 0, v163, s[58:59]
	v_cvt_pk_bf16_f32 v164, v160, v161
	v_cvt_pk_bf16_f32 v165, v162, v163
	ds_write_b64 v189, v[164:165] offset:0
	s_cmp_lt_u32 s2, 1
	s_cbranch_scc1 .Lm3_skip1
	ds_read_b128 v[152:155], v188 offset:2112
	ds_read_b128 v[156:159], v188 offset:64
	s_cmp_eq_u32 s2, 1
	s_cselect_b64 s[52:53], s[44:45], -1
	s_cselect_b64 s[54:55], s[46:47], -1
	s_cselect_b64 s[56:57], s[48:49], -1
	s_cselect_b64 s[58:59], s[50:51], -1
	s_waitcnt lgkmcnt(0)
	v_sub_f32_e32 v160, v206, v152
	v_sub_f32_e32 v161, v206, v153
	v_sub_f32_e32 v162, v206, v154
	v_sub_f32_e32 v163, v206, v155
	v_min_f32_e32 v160, 0, v160
	v_min_f32_e32 v161, 0, v161
	v_min_f32_e32 v162, 0, v162
	v_min_f32_e32 v163, 0, v163
	v_mul_f32_e32 v160, 0x3fb8aa3b, v160
	v_mul_f32_e32 v161, 0x3fb8aa3b, v161
	v_mul_f32_e32 v162, 0x3fb8aa3b, v162
	v_mul_f32_e32 v163, 0x3fb8aa3b, v163
	v_exp_f32_e32 v160, v160
	v_exp_f32_e32 v161, v161
	v_exp_f32_e32 v162, v162
	v_exp_f32_e32 v163, v163
	s_nop 0
	v_mul_f32_e32 v160, v4, v160
	v_mul_f32_e32 v161, v5, v161
	v_mul_f32_e32 v162, v6, v162
	v_mul_f32_e32 v163, v7, v163
	v_mul_f32_e32 v160, v160, v156
	v_mul_f32_e32 v161, v161, v157
	v_mul_f32_e32 v162, v162, v158
	v_mul_f32_e32 v163, v163, v159
	v_cndmask_b32_e64 v160, 0, v160, s[52:53]
	v_cndmask_b32_e64 v161, 0, v161, s[54:55]
	v_cndmask_b32_e64 v162, 0, v162, s[56:57]
	v_cndmask_b32_e64 v163, 0, v163, s[58:59]
	v_cvt_pk_bf16_f32 v164, v160, v161
	v_cvt_pk_bf16_f32 v165, v162, v163
	ds_write_b64 v189, v[164:165] offset:32
	s_cmp_lt_u32 s2, 2
	s_cbranch_scc1 .Lm3_skip2
	ds_read_b128 v[152:155], v188 offset:2176
	ds_read_b128 v[156:159], v188 offset:128
	s_cmp_eq_u32 s2, 2
	s_cselect_b64 s[52:53], s[44:45], -1
	s_cselect_b64 s[54:55], s[46:47], -1
	s_cselect_b64 s[56:57], s[48:49], -1
	s_cselect_b64 s[58:59], s[50:51], -1
	s_waitcnt lgkmcnt(0)
	v_sub_f32_e32 v160, v206, v152
	v_sub_f32_e32 v161, v206, v153
	v_sub_f32_e32 v162, v206, v154
	v_sub_f32_e32 v163, v206, v155
	v_min_f32_e32 v160, 0, v160
	v_min_f32_e32 v161, 0, v161
	v_min_f32_e32 v162, 0, v162
	v_min_f32_e32 v163, 0, v163
	v_mul_f32_e32 v160, 0x3fb8aa3b, v160
	v_mul_f32_e32 v161, 0x3fb8aa3b, v161
	v_mul_f32_e32 v162, 0x3fb8aa3b, v162
	v_mul_f32_e32 v163, 0x3fb8aa3b, v163
	v_exp_f32_e32 v160, v160
	v_exp_f32_e32 v161, v161
	v_exp_f32_e32 v162, v162
	v_exp_f32_e32 v163, v163
	s_nop 0
	v_mul_f32_e32 v160, v8, v160
	v_mul_f32_e32 v161, v9, v161
	v_mul_f32_e32 v162, v10, v162
	v_mul_f32_e32 v163, v11, v163
	v_mul_f32_e32 v160, v160, v156
	v_mul_f32_e32 v161, v161, v157
	v_mul_f32_e32 v162, v162, v158
	v_mul_f32_e32 v163, v163, v159
	v_cndmask_b32_e64 v160, 0, v160, s[52:53]
	v_cndmask_b32_e64 v161, 0, v161, s[54:55]
	v_cndmask_b32_e64 v162, 0, v162, s[56:57]
	v_cndmask_b32_e64 v163, 0, v163, s[58:59]
	v_cvt_pk_bf16_f32 v164, v160, v161
	v_cvt_pk_bf16_f32 v165, v162, v163
	ds_write_b64 v189, v[164:165] offset:64
	s_cmp_lt_u32 s2, 3
	s_cbranch_scc1 .Lm3_skip3
	ds_read_b128 v[152:155], v188 offset:2240
	ds_read_b128 v[156:159], v188 offset:192
	s_cmp_eq_u32 s2, 3
	s_cselect_b64 s[52:53], s[44:45], -1
	s_cselect_b64 s[54:55], s[46:47], -1
	s_cselect_b64 s[56:57], s[48:49], -1
	s_cselect_b64 s[58:59], s[50:51], -1
	s_waitcnt lgkmcnt(0)
	v_sub_f32_e32 v160, v206, v152
	v_sub_f32_e32 v161, v206, v153
	v_sub_f32_e32 v162, v206, v154
	v_sub_f32_e32 v163, v206, v155
	v_min_f32_e32 v160, 0, v160
	v_min_f32_e32 v161, 0, v161
	v_min_f32_e32 v162, 0, v162
	v_min_f32_e32 v163, 0, v163
	v_mul_f32_e32 v160, 0x3fb8aa3b, v160
	v_mul_f32_e32 v161, 0x3fb8aa3b, v161
	v_mul_f32_e32 v162, 0x3fb8aa3b, v162
	v_mul_f32_e32 v163, 0x3fb8aa3b, v163
	v_exp_f32_e32 v160, v160
	v_exp_f32_e32 v161, v161
	v_exp_f32_e32 v162, v162
	v_exp_f32_e32 v163, v163
	s_nop 0
	v_mul_f32_e32 v160, v12, v160
	v_mul_f32_e32 v161, v13, v161
	v_mul_f32_e32 v162, v14, v162
	v_mul_f32_e32 v163, v15, v163
	v_mul_f32_e32 v160, v160, v156
	v_mul_f32_e32 v161, v161, v157
	v_mul_f32_e32 v162, v162, v158
	v_mul_f32_e32 v163, v163, v159
	v_cndmask_b32_e64 v160, 0, v160, s[52:53]
	v_cndmask_b32_e64 v161, 0, v161, s[54:55]
	v_cndmask_b32_e64 v162, 0, v162, s[56:57]
	v_cndmask_b32_e64 v163, 0, v163, s[58:59]
	v_cvt_pk_bf16_f32 v164, v160, v161
	v_cvt_pk_bf16_f32 v165, v162, v163
	ds_write_b64 v189, v[164:165] offset:96
	s_cmp_lt_u32 s2, 4
	s_cbranch_scc1 .Lm3_skip4
; DI unsigned short f2bf(float f) { return (unsigned short)(pk2(f, 0.f) & 0xffffu); }
; __global__ void __launch_bounds__(512, 2) fwd_megakernel(Args args) {
;     ...
;                         for (int st = 0; st < 8; ++st) {
;                             if (st <= (wave | 1)) {
;                                 const int sI = 16 * st + r16; const float acss = hacs[sI], dts = hdt[sI];
; #pragma unroll
;                                 for (int j = 0; j < 4; ++j) { const int l = 16 * wave + q4 * 4 + j; const float mv = (sI <= l) ? cbr[st][j] * __expf(fminf(acl[j] - acss, 0.f)) * dts : 0.f; Ms[l * 136 + sI] = f2bf(mv); }
;                             }
	ds_read_b128 v[152:155], v188 offset:2304
	ds_read_b128 v[156:159], v188 offset:256
	s_cmp_eq_u32 s2, 4
	s_cselect_b64 s[52:53], s[44:45], -1
	s_cselect_b64 s[54:55], s[46:47], -1
	s_cselect_b64 s[56:57], s[48:49], -1
	s_cselect_b64 s[58:59], s[50:51], -1
	s_waitcnt lgkmcnt(0)
	v_sub_f32_e32 v160, v206, v152
	v_sub_f32_e32 v161, v206, v153
	v_sub_f32_e32 v162, v206, v154
	v_sub_f32_e32 v163, v206, v155
	v_min_f32_e32 v160, 0, v160
	v_min_f32_e32 v161, 0, v161
	v_min_f32_e32 v162, 0, v162
	v_min_f32_e32 v163, 0, v163
	v_mul_f32_e32 v160, 0x3fb8aa3b, v160
	v_mul_f32_e32 v161, 0x3fb8aa3b, v161
	v_mul_f32_e32 v162, 0x3fb8aa3b, v162
	v_mul_f32_e32 v163, 0x3fb8aa3b, v163
	v_exp_f32_e32 v160, v160
	v_exp_f32_e32 v161, v161
	v_exp_f32_e32 v162, v162
	v_exp_f32_e32 v163, v163
	s_nop 0
	v_mul_f32_e32 v160, v16, v160
	v_mul_f32_e32 v161, v17, v161
	v_mul_f32_e32 v162, v18, v162
	v_mul_f32_e32 v163, v19, v163
	v_mul_f32_e32 v160, v160, v156
	v_mul_f32_e32 v161, v161, v157
	v_mul_f32_e32 v162, v162, v158
	v_mul_f32_e32 v163, v163, v159
	v_cndmask_b32_e64 v160, 0, v160, s[52:53]
	v_cndmask_b32_e64 v161, 0, v161, s[54:55]
	v_cndmask_b32_e64 v162, 0, v162, s[56:57]
	v_cndmask_b32_e64 v163, 0, v163, s[58:59]
	v_cvt_pk_bf16_f32 v164, v160, v161
	v_cvt_pk_bf16_f32 v165, v162, v163
	ds_write_b64 v189, v[164:165] offset:128
	s_cmp_lt_u32 s2, 5
	s_cbranch_scc1 .Lm3_skip5
	ds_read_b128 v[152:155], v188 offset:2368
	ds_read_b128 v[156:159], v188 offset:320
	s_cmp_eq_u32 s2, 5
	s_cselect_b64 s[52:53], s[44:45], -1
	s_cselect_b64 s[54:55], s[46:47], -1
	s_cselect_b64 s[56:57], s[48:49], -1
	s_cselect_b64 s[58:59], s[50:51], -1
	s_waitcnt lgkmcnt(0)
	v_sub_f32_e32 v160, v206, v152
	v_sub_f32_e32 v161, v206, v153
	v_sub_f32_e32 v162, v206, v154
	v_sub_f32_e32 v163, v206, v155
	v_min_f32_e32 v160, 0, v160
	v_min_f32_e32 v161, 0, v161
	v_min_f32_e32 v162, 0, v162
	v_min_f32_e32 v163, 0, v163
	v_mul_f32_e32 v160, 0x3fb8aa3b, v160
	v_mul_f32_e32 v161, 0x3fb8aa3b, v161
	v_mul_f32_e32 v162, 0x3fb8aa3b, v162
	v_mul_f32_e32 v163, 0x3fb8aa3b, v163
	v_exp_f32_e32 v160, v160
	v_exp_f32_e32 v161, v161
	v_exp_f32_e32 v162, v162
	v_exp_f32_e32 v163, v163
	s_nop 0
	v_mul_f32_e32 v160, v20, v160
	v_mul_f32_e32 v161, v21, v161
	v_mul_f32_e32 v162, v22, v162
	v_mul_f32_e32 v163, v23, v163
	v_mul_f32_e32 v160, v160, v156
	v_mul_f32_e32 v161, v161, v157
	v_mul_f32_e32 v162, v162, v158
	v_mul_f32_e32 v163, v163, v159
	v_cndmask_b32_e64 v160, 0, v160, s[52:53]
	v_cndmask_b32_e64 v161, 0, v161, s[54:55]
	v_cndmask_b32_e64 v162, 0, v162, s[56:57]
	v_cndmask_b32_e64 v163, 0, v163, s[58:59]
	v_cvt_pk_bf16_f32 v164, v160, v161
	v_cvt_pk_bf16_f32 v165, v162, v163
	ds_write_b64 v189, v[164:165] offset:160
	s_cmp_lt_u32 s2, 6
	s_cbranch_scc1 .Lm3_skip6
	ds_read_b128 v[152:155], v188 offset:2432
	ds_read_b128 v[156:159], v188 offset:384
	s_cmp_eq_u32 s2, 6
	s_cselect_b64 s[52:53], s[44:45], -1
	s_cselect_b64 s[54:55], s[46:47], -1
	s_cselect_b64 s[56:57], s[48:49], -1
	s_cselect_b64 s[58:59], s[50:51], -1
	s_waitcnt lgkmcnt(0)
	v_sub_f32_e32 v160, v206, v152
	v_sub_f32_e32 v161, v206, v153
	v_sub_f32_e32 v162, v206, v154
	v_sub_f32_e32 v163, v206, v155
	v_min_f32_e32 v160, 0, v160
	v_min_f32_e32 v161, 0, v161
	v_min_f32_e32 v162, 0, v162
	v_min_f32_e32 v163, 0, v163
	v_mul_f32_e32 v160, 0x3fb8aa3b, v160
	v_mul_f32_e32 v161, 0x3fb8aa3b, v161
	v_mul_f32_e32 v162, 0x3fb8aa3b, v162
	v_mul_f32_e32 v163, 0x3fb8aa3b, v163
	v_exp_f32_e32 v160, v160
	v_exp_f32_e32 v161, v161
	v_exp_f32_e32 v162, v162
	v_exp_f32_e32 v163, v163
	s_nop 0
	v_mul_f32_e32 v160, v24, v160
	v_mul_f32_e32 v161, v25, v161
	v_mul_f32_e32 v162, v26, v162
	v_mul_f32_e32 v163, v27, v163
	v_mul_f32_e32 v160, v160, v156
	v_mul_f32_e32 v161, v161, v157
	v_mul_f32_e32 v162, v162, v158
	v_mul_f32_e32 v163, v163, v159
	v_cndmask_b32_e64 v160, 0, v160, s[52:53]
	v_cndmask_b32_e64 v161, 0, v161, s[54:55]
	v_cndmask_b32_e64 v162, 0, v162, s[56:57]
	v_cndmask_b32_e64 v163, 0, v163, s[58:59]
	v_cvt_pk_bf16_f32 v164, v160, v161
	v_cvt_pk_bf16_f32 v165, v162, v163
	ds_write_b64 v189, v[164:165] offset:192
	s_cmp_lt_u32 s2, 7
	s_cbranch_scc1 .Lm3_skip7
	ds_read_b128 v[152:155], v188 offset:2496
	ds_read_b128 v[156:159], v188 offset:448
	s_cmp_eq_u32 s2, 7
	s_cselect_b64 s[52:53], s[44:45], -1
	s_cselect_b64 s[54:55], s[46:47], -1
	s_cselect_b64 s[56:57], s[48:49], -1
	s_cselect_b64 s[58:59], s[50:51], -1
	s_waitcnt lgkmcnt(0)
	v_sub_f32_e32 v160, v206, v152
	v_sub_f32_e32 v161, v206, v153
	v_sub_f32_e32 v162, v206, v154
	v_sub_f32_e32 v163, v206, v155
	v_min_f32_e32 v160, 0, v160
	v_min_f32_e32 v161, 0, v161
	v_min_f32_e32 v162, 0, v162
	v_min_f32_e32 v163, 0, v163
	v_mul_f32_e32 v160, 0x3fb8aa3b, v160
	v_mul_f32_e32 v161, 0x3fb8aa3b, v161
	v_mul_f32_e32 v162, 0x3fb8aa3b, v162
	v_mul_f32_e32 v163, 0x3fb8aa3b, v163
	v_exp_f32_e32 v160, v160
	v_exp_f32_e32 v161, v161
	v_exp_f32_e32 v162, v162
	v_exp_f32_e32 v163, v163
	s_nop 0
	v_mul_f32_e32 v160, v28, v160
	v_mul_f32_e32 v161, v29, v161
	v_mul_f32_e32 v162, v30, v162
	v_mul_f32_e32 v163, v31, v163
	v_mul_f32_e32 v160, v160, v156
	v_mul_f32_e32 v161, v161, v157
	v_mul_f32_e32 v162, v162, v158
	v_mul_f32_e32 v163, v163, v159
	v_cndmask_b32_e64 v160, 0, v160, s[52:53]
	v_cndmask_b32_e64 v161, 0, v161, s[54:55]
	v_cndmask_b32_e64 v162, 0, v162, s[56:57]
	v_cndmask_b32_e64 v163, 0, v163, s[58:59]
	v_cvt_pk_bf16_f32 v164, v160, v161
	v_cvt_pk_bf16_f32 v165, v162, v163
	ds_write_b64 v189, v[164:165] offset:224
	s_branch .Lm3_msdone

; __global__ void __launch_bounds__(512, 2) fwd_megakernel(Args args) {
;     ...
;                         bf16x8 pvf[4][4];
;                         {
;                             const bf16* pv = PV + (size_t)unit8 * 8192;
; #pragma unroll
;                             for (int ks = 0; ks < 4; ++ks)
; #pragma unroll
;                                 for (int pt = 0; pt < 4; ++pt) pvf[ks][pt] = *(const bf16x8*)(pv + (16 * pt + r16) * 128 + ks * 32 + q4 * 8);
;                         }
;                         bf16 zr[4][4];
; #pragma unroll
;                         for (int j = 0; j < 4; ++j)
; #pragma unroll
;                             for (int pt = 0; pt < 4; ++pt) zr[j][pt] = proj[(grow0 + 16 * wave + q4 * 4 + j) * NPROJ + PC_Z + h * 64 + 16 * pt + r16];
;                         const LAS float* hdt = s_dt + hh * 128; const LAS float* hacs = s_acs + hh * 128;
;                         float acl[4];
; #pragma unroll
;                         for (int j = 0; j < 4; ++j) acl[j] = hacs[16 * wave + q4 * 4 + j];
; #pragma unroll
;                         for (int st = 0; st < 8; ++st) {
;                             if (st <= (wave | 1)) {
;                                 const int sI = 16 * st + r16; const float acss = hacs[sI], dts = hdt[sI];
; #pragma unroll
;                                 for (int j = 0; j < 4; ++j) { const int l = 16 * wave + q4 * 4 + j; const float mv = (sI <= l) ? cbr[st][j] * __expf(fminf(acl[j] - acss, 0.f)) * dts : 0.f; Ms[l * 136 + sI] = f2bf(mv); }
;                             }
;                         }
;                         f32x4 yo[4], yd[4];
; #pragma unroll
;                         for (int pt = 0; pt < 4; ++pt) { yo[pt] = (f32x4){0.f, 0.f, 0.f, 0.f}; yd[pt] = (f32x4){0.f, 0.f, 0.f, 0.f}; }
;                         const LAS bf16* xh = xT + hh * (64 * 136);
; #pragma unroll
;                         for (int ks = 0; ks < 4; ++ks) {
;                             if (2 * ks <= wave) {
;                                 const bf16x8 ma = lds_frag(Ms, lrow, 136, ks * 32 + q4 * 8);
; #pragma unroll
;                                 for (int pt = 0; pt < 4; ++pt) yd[pt] = mfma16(ma, lds_frag(xh, 16 * pt + r16, 136, ks * 32 + q4 * 8), yd[pt]);
;                             }
;                         }
; #pragma unroll
;                         for (int ks = 0; ks < 4; ++ks)
; #pragma unroll
.Lm3_msdone:
	v_mul_f32_e32 v207, 0x3fb8aa3b, v206
	v_exp_f32_e32 v207, v207
	ds_read_u16 v136, v191 offset:0
	ds_read_u16 v137, v191 offset:272
	ds_read_u16 v138, v191 offset:544
	ds_read_u16 v139, v191 offset:816
	ds_read_u16 v140, v191 offset:4352
	ds_read_u16 v141, v191 offset:4624
	ds_read_u16 v142, v191 offset:4896
	ds_read_u16 v143, v191 offset:5168
	ds_read_u16 v144, v191 offset:8704
	ds_read_u16 v145, v191 offset:8976
	ds_read_u16 v146, v191 offset:9248
	ds_read_u16 v147, v191 offset:9520
	ds_read_u16 v148, v191 offset:13056
	ds_read_u16 v149, v191 offset:13328
	ds_read_u16 v150, v191 offset:13600
	ds_read_u16 v151, v191 offset:13872
	s_waitcnt lgkmcnt(0)
	s_barrier
	v_add_u32_e32 v180, s28, v178
	ds_read_b128 v[48:51], v180 offset:0
	ds_read_b128 v[52:55], v180 offset:4352
	ds_read_b128 v[56:59], v180 offset:8704
	ds_read_b128 v[60:63], v180 offset:13056
	ds_read_b128 v[64:67], v180 offset:64
	ds_read_b128 v[68:71], v180 offset:4416
	ds_read_b128 v[72:75], v180 offset:8768
	ds_read_b128 v[76:79], v180 offset:13120
	ds_read_b128 v[80:83], v180 offset:128
	ds_read_b128 v[84:87], v180 offset:4480
	ds_read_b128 v[88:91], v180 offset:8832
	ds_read_b128 v[92:95], v180 offset:13184
	ds_read_b128 v[96:99], v180 offset:192
	ds_read_b128 v[100:103], v180 offset:4544
	ds_read_b128 v[104:107], v180 offset:8896
	ds_read_b128 v[108:111], v180 offset:13248
	s_waitcnt lgkmcnt(0)
	v_mfma_f32_16x16x32_bf16 v[112:115], v[48:51], v[32:35], 0
	v_mfma_f32_16x16x32_bf16 v[116:119], v[52:55], v[32:35], 0
	v_mfma_f32_16x16x32_bf16 v[120:123], v[56:59], v[32:35], 0
	v_mfma_f32_16x16x32_bf16 v[124:127], v[60:63], v[32:35], 0
	v_mfma_f32_16x16x32_bf16 v[112:115], v[64:67], v[36:39], v[112:115]
	v_mfma_f32_16x16x32_bf16 v[116:119], v[68:71], v[36:39], v[116:119]
	v_mfma_f32_16x16x32_bf16 v[120:123], v[72:75], v[36:39], v[120:123]
	v_mfma_f32_16x16x32_bf16 v[124:127], v[76:79], v[36:39], v[124:127]
	v_mfma_f32_16x16x32_bf16 v[112:115], v[80:83], v[40:43], v[112:115]
	v_mfma_f32_16x16x32_bf16 v[116:119], v[84:87], v[40:43], v[116:119]
	v_mfma_f32_16x16x32_bf16 v[120:123], v[88:91], v[40:43], v[120:123]
	v_mfma_f32_16x16x32_bf16 v[124:127], v[92:95], v[40:43], v[124:127]
	v_mfma_f32_16x16x32_bf16 v[112:115], v[96:99], v[44:47], v[112:115]
	v_mfma_f32_16x16x32_bf16 v[116:119], v[100:103], v[44:47], v[116:119]
	v_mfma_f32_16x16x32_bf16 v[120:123], v[104:107], v[44:47], v[120:123]
	v_mfma_f32_16x16x32_bf16 v[124:127], v[108:111], v[44:47], v[124:127]
	s_nop 7
	s_nop 3
	v_mul_f32_e32 v112, v207, v112
	v_mul_f32_e32 v113, v207, v113
	v_mul_f32_e32 v114, v207, v114
	v_mul_f32_e32 v115, v207, v115
	v_mul_f32_e32 v116, v207, v116
	v_mul_f32_e32 v117, v207, v117
	v_mul_f32_e32 v118, v207, v118
	v_mul_f32_e32 v119, v207, v119
	v_mul_f32_e32 v120, v207, v120
	v_mul_f32_e32 v121, v207, v121
	v_mul_f32_e32 v122, v207, v122
	v_mul_f32_e32 v123, v207, v123
	v_mul_f32_e32 v124, v207, v124
	v_mul_f32_e32 v125, v207, v125
	v_mul_f32_e32 v126, v207, v126
	v_mul_f32_e32 v127, v207, v127
	s_waitcnt lgkmcnt(0)
	ds_read_b128 v[160:163], v179 offset:34816
	ds_read_b128 v[164:167], v190 offset:0
	ds_read_b128 v[168:171], v190 offset:4352
	ds_read_b128 v[172:175], v190 offset:8704
	ds_read_b128 v[152:155], v190 offset:13056
	s_waitcnt lgkmcnt(0)
	v_mfma_f32_16x16x32_bf16 v[112:115], v[164:167], v[160:163], v[112:115]
	v_mfma_f32_16x16x32_bf16 v[116:119], v[168:171], v[160:163], v[116:119]
	v_mfma_f32_16x16x32_bf16 v[120:123], v[172:175], v[160:163], v[120:123]
	v_mfma_f32_16x16x32_bf16 v[124:127], v[152:155], v[160:163], v[124:127]
	s_cmp_lt_u32 s2, 2
	s_cbranch_scc1 .Lm3_yddone
	ds_read_b128 v[160:163], v179 offset:34880
	ds_read_b128 v[164:167], v190 offset:64
	ds_read_b128 v[168:171], v190 offset:4416
	ds_read_b128 v[172:175], v190 offset:8768
	ds_read_b128 v[152:155], v190 offset:13120
	s_waitcnt lgkmcnt(0)
	v_mfma_f32_16x16x32_bf16 v[112:115], v[164:167], v[160:163], v[112:115]
	v_mfma_f32_16x16x32_bf16 v[116:119], v[168:171], v[160:163], v[116:119]
	v_mfma_f32_16x16x32_bf16 v[120:123], v[172:175], v[160:163], v[120:123]
	v_mfma_f32_16x16x32_bf16 v[124:127], v[152:155], v[160:163], v[124:127]
	s_cmp_lt_u32 s2, 4
	s_cbranch_scc1 .Lm3_yddone
	ds_read_b128 v[160:163], v179 offset:34944
	ds_read_b128 v[164:167], v190 offset:128
	ds_read_b128 v[168:171], v190 offset:4480
	ds_read_b128 v[172:175], v190 offset:8832
	ds_read_b128 v[152:155], v190 offset:13184
	s_waitcnt lgkmcnt(0)
	v_mfma_f32_16x16x32_bf16 v[112:115], v[164:167], v[160:163], v[112:115]
	v_mfma_f32_16x16x32_bf16 v[116:119], v[168:171], v[160:163], v[116:119]
	v_mfma_f32_16x16x32_bf16 v[120:123], v[172:175], v[160:163], v[120:123]
	v_mfma_f32_16x16x32_bf16 v[124:127], v[152:155], v[160:163], v[124:127]
	s_cmp_lt_u32 s2, 6
	s_cbranch_scc1 .Lm3_yddone
	ds_read_b128 v[160:163], v179 offset:35008
	ds_read_b128 v[164:167], v190 offset:192
	ds_read_b128 v[168:171], v190 offset:4544
	ds_read_b128 v[172:175], v190 offset:8896
	ds_read_b128 v[152:155], v190 offset:13248
	s_waitcnt lgkmcnt(0)
	v_mfma_f32_16x16x32_bf16 v[112:115], v[164:167], v[160:163], v[112:115]
	v_mfma_f32_16x16x32_bf16 v[116:119], v[168:171], v[160:163], v[116:119]
	v_mfma_f32_16x16x32_bf16 v[120:123], v[172:175], v[160:163], v[120:123]
	v_mfma_f32_16x16x32_bf16 v[124:127], v[152:155], v[160:163], v[124:127]
.Lm3_yddone:
	s_waitcnt vmcnt(0)
	s_cmp_eq_u32 s3, 3
	s_cbranch_scc1 .Lm3_nost
	s_xor_b32 s29, s28, 0x4400
	v_add_u32_e32 v181, s29, v183
	ds_write_b128 v181, v[196:199]
	ds_write_b128 v181, v[234:237] offset:1088
; DI float bf2f(unsigned short b) { return __uint_as_float((unsigned)b << 16); }
; DI unsigned short f2bf(float f) { return (unsigned short)(pk2(f, 0.f) & 0xffffu); }
; DI float silu_f(float x) { return x * fast_sigmoid(x); }
; DI float sum16(float v) { v += __shfl_xor(v, 1); v += __shfl_xor(v, 2); v += __shfl_xor(v, 4); v += __shfl_xor(v, 8); return v; }
; __global__ void __launch_bounds__(512, 2) fwd_megakernel(Args args) {
;     ...
;                     for (int hh = 0; hh < 4; ++hh) {
;                         const int h = g2 * 4 + hh; const int unit8 = ((b * NCH + c) * 8) + h;
;     ...
;                         const float Dh = args.in[11][layer * 8 + h];
; #pragma unroll
;                         for (int j = 0; j < 4; ++j) {
;                             const int l = 16 * wave + q4 * 4 + j; const size_t row = grow0 + l; const float ea = __expf(acl[j]); float ss = 0.f;
; #pragma unroll
;                             for (int pt = 0; pt < 4; ++pt) {
;                                 const int p = 16 * pt + r16;
;                                 const float y = yd[pt][j] + ea * yo[pt][j] + Dh * bf2f(xh[p * 136 + l]);
;                                 const float o = y * silu_f(bf2f(zr[j][pt])); ss += o * o; Yg[row * DM + h * 64 + p] = f2bf(o);
;                             }
;                             ss = sum16(ss);
;                             if (r16 == 0) mss_g[((size_t)g2 * MTOK + row) * 4 + hh] = ss;
;                         }
.Lm3_nost:
	s_nop 7
	s_nop 3
	v_lshlrev_b32_e32 v160, 16, v128
	v_and_b32_e32 v161, 0xffff0000, v128
	v_lshlrev_b32_e32 v162, 16, v129
	v_and_b32_e32 v163, 0xffff0000, v129
	v_lshlrev_b32_e32 v136, 16, v136
	v_lshlrev_b32_e32 v137, 16, v137
	v_lshlrev_b32_e32 v138, 16, v138
	v_lshlrev_b32_e32 v139, 16, v139
	v_fmac_f32_e32 v112, s36, v136
	v_fmac_f32_e32 v113, s36, v137
	v_fmac_f32_e32 v114, s36, v138
	v_fmac_f32_e32 v115, s36, v139
	v_mul_f32_e32 v164, 0xbfb8aa3b, v160
	v_mul_f32_e32 v165, 0xbfb8aa3b, v161
	v_mul_f32_e32 v166, 0xbfb8aa3b, v162
	v_mul_f32_e32 v167, 0xbfb8aa3b, v163
	v_exp_f32_e32 v164, v164
	v_exp_f32_e32 v165, v165
	v_exp_f32_e32 v166, v166
	v_exp_f32_e32 v167, v167
	s_nop 0
	v_add_f32_e32 v164, 1.0, v164
	v_add_f32_e32 v165, 1.0, v165
	v_add_f32_e32 v166, 1.0, v166
	v_add_f32_e32 v167, 1.0, v167
	v_rcp_f32_e32 v164, v164
	v_rcp_f32_e32 v165, v165
	v_rcp_f32_e32 v166, v166
	v_rcp_f32_e32 v167, v167
	s_nop 0
	v_mul_f32_e32 v164, v164, v160
	v_mul_f32_e32 v165, v165, v161
	v_mul_f32_e32 v166, v166, v162
	v_mul_f32_e32 v167, v167, v163
	v_mul_f32_e32 v164, v112, v164
	v_mul_f32_e32 v165, v113, v165
	v_mul_f32_e32 v166, v114, v166
	v_mul_f32_e32 v167, v115, v167
	v_mul_f32_e32 v208, v164, v164
	v_fmac_f32_e32 v208, v165, v165
	v_fmac_f32_e32 v208, v166, v166
	v_fmac_f32_e32 v208, v167, v167
	v_cvt_pk_bf16_f32 v168, v164, v165
	v_cvt_pk_bf16_f32 v169, v166, v167
	global_store_dwordx2 v185, v[168:169], s[12:13] offset:0
	v_lshlrev_b32_e32 v160, 16, v130
	v_and_b32_e32 v161, 0xffff0000, v130
	v_lshlrev_b32_e32 v162, 16, v131
	v_and_b32_e32 v163, 0xffff0000, v131
	v_lshlrev_b32_e32 v140, 16, v140
	v_lshlrev_b32_e32 v141, 16, v141
	v_lshlrev_b32_e32 v142, 16, v142
	v_lshlrev_b32_e32 v143, 16, v143
	v_fmac_f32_e32 v116, s36, v140
	v_fmac_f32_e32 v117, s36, v141
	v_fmac_f32_e32 v118, s36, v142
	v_fmac_f32_e32 v119, s36, v143
	v_mul_f32_e32 v164, 0xbfb8aa3b, v160
	v_mul_f32_e32 v165, 0xbfb8aa3b, v161
	v_mul_f32_e32 v166, 0xbfb8aa3b, v162
	v_mul_f32_e32 v167, 0xbfb8aa3b, v163
	v_exp_f32_e32 v164, v164
	v_exp_f32_e32 v165, v165
	v_exp_f32_e32 v166, v166
	v_exp_f32_e32 v167, v167
	s_nop 0
	v_add_f32_e32 v164, 1.0, v164
	v_add_f32_e32 v165, 1.0, v165
	v_add_f32_e32 v166, 1.0, v166
	v_add_f32_e32 v167, 1.0, v167
	v_rcp_f32_e32 v164, v164
	v_rcp_f32_e32 v165, v165
	v_rcp_f32_e32 v166, v166
	v_rcp_f32_e32 v167, v167
	s_nop 0
	v_mul_f32_e32 v164, v164, v160
	v_mul_f32_e32 v165, v165, v161
	v_mul_f32_e32 v166, v166, v162
	v_mul_f32_e32 v167, v167, v163
	v_mul_f32_e32 v164, v116, v164
	v_mul_f32_e32 v165, v117, v165
	v_mul_f32_e32 v166, v118, v166
	v_mul_f32_e32 v167, v119, v167
	v_fmac_f32_e32 v208, v164, v164
	v_fmac_f32_e32 v208, v165, v165
	v_fmac_f32_e32 v208, v166, v166
	v_fmac_f32_e32 v208, v167, v167
	v_cvt_pk_bf16_f32 v168, v164, v165
	v_cvt_pk_bf16_f32 v169, v166, v167
	global_store_dwordx2 v185, v[168:169], s[12:13] offset:32
	v_lshlrev_b32_e32 v160, 16, v132
	v_and_b32_e32 v161, 0xffff0000, v132
	v_lshlrev_b32_e32 v162, 16, v133
	v_and_b32_e32 v163, 0xffff0000, v133
	v_lshlrev_b32_e32 v144, 16, v144
	v_lshlrev_b32_e32 v145, 16, v145
	v_lshlrev_b32_e32 v146, 16, v146
	v_lshlrev_b32_e32 v147, 16, v147
	v_fmac_f32_e32 v120, s36, v144
	v_fmac_f32_e32 v121, s36, v145
	v_fmac_f32_e32 v122, s36, v146
	v_fmac_f32_e32 v123, s36, v147
	v_mul_f32_e32 v164, 0xbfb8aa3b, v160
	v_mul_f32_e32 v165, 0xbfb8aa3b, v161
	v_mul_f32_e32 v166, 0xbfb8aa3b, v162
	v_mul_f32_e32 v167, 0xbfb8aa3b, v163
	v_exp_f32_e32 v164, v164
	v_exp_f32_e32 v165, v165
	v_exp_f32_e32 v166, v166
	v_exp_f32_e32 v167, v167
	s_nop 0
	v_add_f32_e32 v164, 1.0, v164
	v_add_f32_e32 v165, 1.0, v165
	v_add_f32_e32 v166, 1.0, v166
	v_add_f32_e32 v167, 1.0, v167
	v_rcp_f32_e32 v164, v164
	v_rcp_f32_e32 v165, v165
	v_rcp_f32_e32 v166, v166
	v_rcp_f32_e32 v167, v167
	s_nop 0
	v_mul_f32_e32 v164, v164, v160
	v_mul_f32_e32 v165, v165, v161
	v_mul_f32_e32 v166, v166, v162
	v_mul_f32_e32 v167, v167, v163
	v_mul_f32_e32 v164, v120, v164
	v_mul_f32_e32 v165, v121, v165
	v_mul_f32_e32 v166, v122, v166
	v_mul_f32_e32 v167, v123, v167
	v_fmac_f32_e32 v208, v164, v164
	v_fmac_f32_e32 v208, v165, v165
	v_fmac_f32_e32 v208, v166, v166
	v_fmac_f32_e32 v208, v167, v167
	v_cvt_pk_bf16_f32 v168, v164, v165
	v_cvt_pk_bf16_f32 v169, v166, v167
	global_store_dwordx2 v185, v[168:169], s[12:13] offset:64
	v_lshlrev_b32_e32 v160, 16, v134
	v_and_b32_e32 v161, 0xffff0000, v134
	v_lshlrev_b32_e32 v162, 16, v135
	v_and_b32_e32 v163, 0xffff0000, v135
	v_lshlrev_b32_e32 v148, 16, v148
	v_lshlrev_b32_e32 v149, 16, v149
	v_lshlrev_b32_e32 v150, 16, v150
	v_lshlrev_b32_e32 v151, 16, v151
	v_fmac_f32_e32 v124, s36, v148
	v_fmac_f32_e32 v125, s36, v149
	v_fmac_f32_e32 v126, s36, v150
	v_fmac_f32_e32 v127, s36, v151
	v_mul_f32_e32 v164, 0xbfb8aa3b, v160
	v_mul_f32_e32 v165, 0xbfb8aa3b, v161
	v_mul_f32_e32 v166, 0xbfb8aa3b, v162
	v_mul_f32_e32 v167, 0xbfb8aa3b, v163
	v_exp_f32_e32 v164, v164
	v_exp_f32_e32 v165, v165
	v_exp_f32_e32 v166, v166
	v_exp_f32_e32 v167, v167
	s_nop 0
	v_add_f32_e32 v164, 1.0, v164
	v_add_f32_e32 v165, 1.0, v165
	v_add_f32_e32 v166, 1.0, v166
	v_add_f32_e32 v167, 1.0, v167
	v_rcp_f32_e32 v164, v164
	v_rcp_f32_e32 v165, v165
	v_rcp_f32_e32 v166, v166
	v_rcp_f32_e32 v167, v167
	s_nop 0
	v_mul_f32_e32 v164, v164, v160
	v_mul_f32_e32 v165, v165, v161
	v_mul_f32_e32 v166, v166, v162
	v_mul_f32_e32 v167, v167, v163
	v_mul_f32_e32 v164, v124, v164
	v_mul_f32_e32 v165, v125, v165
	v_mul_f32_e32 v166, v126, v166
	v_mul_f32_e32 v167, v127, v167
	v_fmac_f32_e32 v208, v164, v164
	v_fmac_f32_e32 v208, v165, v165
	v_fmac_f32_e32 v208, v166, v166
	v_fmac_f32_e32 v208, v167, v167
	v_cvt_pk_bf16_f32 v168, v164, v165
	v_cvt_pk_bf16_f32 v169, v166, v167
	global_store_dwordx2 v185, v[168:169], s[12:13] offset:96
	ds_bpermute_b32 v213, v211, v208
	s_waitcnt lgkmcnt(0)
	v_add_f32_e32 v208, v208, v213
	ds_bpermute_b32 v213, v212, v208
	s_waitcnt lgkmcnt(0)
	v_add_f32_e32 v208, v208, v213
	s_mov_b64 exec, s[42:43]
	global_store_dword v186, v208, s[22:23]
	s_mov_b64 exec, -1
	s_cmp_eq_u32 s3, 3
	s_cbranch_scc1 .Lm3_exit
	s_add_u32 s10, s10, 0x80
	s_addc_u32 s11, s11, 0
	global_load_dwordx2 v[128:129], v184, s[10:11] offset:0
	global_load_dwordx2 v[130:131], v184, s[10:11] offset:32
	global_load_dwordx2 v[132:133], v184, s[10:11] offset:64
	global_load_dwordx2 v[134:135], v184, s[10:11] offset:96
	s_add_u32 s12, s12, 0x80
	s_addc_u32 s13, s13, 0
	s_add_u32 s22, s22, 4
	s_addc_u32 s23, s23, 0
	v_add_u32_e32 v187, 0x200, v187
	v_add_u32_e32 v188, 0x200, v188
	v_add_u32_e32 v190, 0x4400, v190
	v_add_u32_e32 v191, 0x4400, v191
	s_mov_b32 s36, s37
	s_mov_b32 s37, s38
	s_mov_b32 s38, s39
	s_xor_b32 s28, s28, 0x4400
	s_add_u32 s34, s34, 0x4000
	s_addc_u32 s35, s35, 0
	s_add_i32 s3, s3, 1
	s_branch .Lm3_head
.Lm3_exit:
	s_branch .LBB0_928
.LBB0_1079:
	s_and_b64 vcc, exec, s[8:9]
	s_cbranch_vccnz .LBB0_1087
